# v64 + 1024 of segment 11's 2816 conversion items also moved into the P4 idle tail (workgroups 0-63); P5 converts the remaining 1792 items one per wave
# speedup vs baseline: 1.0045x; 1.0006x over previous
.Lp4c_done:
	s_waitcnt vmcnt(0) lgkmcnt(0)
	s_barrier
	s_lshl_b32 s12, s82, 3
	s_add_i32 s12, s12, s83
	s_movk_i32 s14, 0x800
	s_mov_b64 s[0:1], s[70:71]
	s_load_dwordx2 s[4:5], s[0:1], 0xb8
	s_lshl_b32 s0, s83, 14
	s_mov_b64 s[6:7], s[70:71]
	s_add_i32 s2, s0, 0
	s_waitcnt lgkmcnt(0)
	v_mbcnt_hi_u32_b32 v168, -1, v187
	s_add_u32 s8, s6, 0x98
	s_addc_u32 s9, s7, 0
	v_lshlrev_b32_e32 v3, 3, v168
	s_add_u32 s16, s6, 0xa8
	v_lshrrev_b32_e32 v42, 3, v168
	v_and_b32_e32 v3, 56, v3
	s_addc_u32 s17, s7, 0
	v_and_b32_e32 v144, 64, v168
	v_mul_u32_u24_e32 v4, 0x84, v3
	v_lshlrev_b32_e32 v32, 2, v42
	s_abs_i32 s15, s14
	v_add_u32_e32 v44, 8, v42
	v_or_b32_e32 v1, v42, v144
	v_add3_u32 v47, s2, v4, v32
	v_cvt_f32_u32_e32 v4, s15
	v_or_b32_e32 v45, 16, v42
	v_lshlrev_b32_e32 v48, 2, v1
	v_or_b32_e32 v1, v44, v144
	v_add_u32_e32 v46, 24, v42
	v_lshlrev_b32_e32 v49, 2, v1
	v_or_b32_e32 v1, v45, v144
	v_lshlrev_b32_e32 v50, 2, v1
	v_or_b32_e32 v1, v46, v144
	v_lshlrev_b32_e32 v51, 2, v1
	v_rcp_iflag_f32_e32 v1, v4
	s_load_dwordx2 s[0:1], s[6:7], 0xb8
	v_mov_b32_e32 v35, 0
	v_lshlrev_b32_e32 v34, 1, v3
	v_mul_f32_e32 v1, 0x4f7ffffe, v1
	v_cvt_u32_f32_e32 v1, v1
	s_waitcnt lgkmcnt(0)
	v_lshl_add_u64 v[36:37], s[0:1], 0, v[34:35]
	s_sub_i32 s0, 0, s15
	v_lshlrev_b32_e32 v0, 2, v168
	v_readfirstlane_b32 s1, v1
	v_add_u32_e32 v2, 56, v42
	s_mul_i32 s0, s0, s1
	v_and_b32_e32 v0, 28, v0
	v_and_or_b32 v2, v2, 63, v144
	s_mul_hi_u32 s0, s1, s0
	s_mov_b32 s13, 0
	v_lshl_add_u32 v33, v0, 2, s2
	v_mul_u32_u24_e32 v43, 0x84, v42
	v_or_b32_e32 v52, 0x80, v48
	v_add_u32_e32 v53, 0xa0, v48
	v_or_b32_e32 v54, 0xc0, v48
	v_lshlrev_b32_e32 v55, 2, v2
	s_add_i32 s33, s1, s0
	s_mov_b32 s34, 0x20000
	s_mov_b64 s[0:1], -1
	s_mov_b64 s[18:19], -1
	v_lshlrev_b32_e32 v34, 2, v0
	s_branch .Lp4d_662

.LBB0_659:
	s_cmp_lt_i32 s81, 6
	s_cselect_b64 s[2:3], -1, 0
	s_and_b64 s[10:11], s[2:3], s[0:1]
	s_andn2_b64 vcc, exec, s[10:11]
	s_cbranch_vccnz .LBB0_831
	s_mov_b32 s100, s12
	s_mov_b32 s101, s14
	s_cmpk_lg_i32 s79, 0x100
	s_cbranch_scc1 .Lp5c_std
	s_movk_i32 s14, 0x1000
	s_cmpk_ge_i32 s12, 0x200
	s_cbranch_scc1 .Lp5c_std
	s_add_i32 s0, s12, 0xa00
	s_cmpk_lt_i32 s12, 0x100
	s_cselect_b32 s12, s0, 0x3fffffff
.Lp5c_std:
	s_mov_b64 s[0:1], s[70:71]
	s_load_dwordx2 s[4:5], s[0:1], 0xb8
	s_lshl_b32 s0, s83, 14
	s_mov_b64 s[6:7], s[70:71]
	s_add_i32 s2, s0, 0
	s_waitcnt lgkmcnt(0)
	v_mbcnt_hi_u32_b32 v168, -1, v187
	s_add_u32 s8, s6, 0x98
	s_addc_u32 s9, s7, 0
	v_lshlrev_b32_e32 v3, 3, v168
	s_add_u32 s16, s6, 0xa8
	v_lshrrev_b32_e32 v42, 3, v168
	v_and_b32_e32 v3, 56, v3
	s_addc_u32 s17, s7, 0
	v_and_b32_e32 v144, 64, v168
	v_mul_u32_u24_e32 v4, 0x84, v3
	v_lshlrev_b32_e32 v32, 2, v42
	s_abs_i32 s15, s14
	v_add_u32_e32 v44, 8, v42
	v_or_b32_e32 v1, v42, v144
	v_add3_u32 v47, s2, v4, v32
	v_cvt_f32_u32_e32 v4, s15
	v_or_b32_e32 v45, 16, v42
	v_lshlrev_b32_e32 v48, 2, v1
	v_or_b32_e32 v1, v44, v144
	v_add_u32_e32 v46, 24, v42
	v_lshlrev_b32_e32 v49, 2, v1
	v_or_b32_e32 v1, v45, v144
	v_lshlrev_b32_e32 v50, 2, v1
	v_or_b32_e32 v1, v46, v144
	v_lshlrev_b32_e32 v51, 2, v1
	v_rcp_iflag_f32_e32 v1, v4
	s_load_dwordx2 s[0:1], s[6:7], 0xb8
	v_mov_b32_e32 v35, 0
	v_lshlrev_b32_e32 v34, 1, v3
	v_mul_f32_e32 v1, 0x4f7ffffe, v1
	v_cvt_u32_f32_e32 v1, v1
	s_waitcnt lgkmcnt(0)
	v_lshl_add_u64 v[36:37], s[0:1], 0, v[34:35]
	s_sub_i32 s0, 0, s15
	v_lshlrev_b32_e32 v0, 2, v168
	v_readfirstlane_b32 s1, v1
	v_add_u32_e32 v2, 56, v42
	s_mul_i32 s0, s0, s1
	v_and_b32_e32 v0, 28, v0
	v_and_or_b32 v2, v2, 63, v144
	s_mul_hi_u32 s0, s1, s0
	s_mov_b32 s13, 0
	v_lshl_add_u32 v33, v0, 2, s2
	v_mul_u32_u24_e32 v43, 0x84, v42
	v_or_b32_e32 v52, 0x80, v48
	v_add_u32_e32 v53, 0xa0, v48
	v_or_b32_e32 v54, 0xc0, v48
	v_lshlrev_b32_e32 v55, 2, v2
	s_add_i32 s33, s1, s0
	s_lshl_b32 s34, s79, 9
	s_cmpk_eq_i32 s79, 0x100
	s_cselect_b32 s34, 0x40000, s34
	s_mov_b64 s[0:1], -1
	s_mov_b64 s[18:19], 0
	s_cmpk_eq_i32 s79, 0x100
	s_cselect_b64 s[18:19], -1, 0
	v_lshlrev_b32_e32 v34, 2, v0
	s_branch .LBB0_662

.LBB0_678:
	s_mov_b32 s12, s100
	s_mov_b32 s14, s101
	s_cmpk_gt_i32 s12, 0x3fff
	s_cbranch_scc1 .LBB0_681
	v_and_b32_e32 v6, 7, v168
	s_ashr_i32 s13, s12, 31
	s_lshl_b64 s[2:3], s[12:13], 10
	v_lshlrev_b32_e32 v4, 4, v6
	v_or_b32_e32 v2, s2, v4
	v_mov_b32_e32 v3, s3
	v_lshlrev_b32_e32 v10, 7, v42
	v_mov_b32_e32 v11, 0
	v_lshl_add_u64 v[2:3], v[2:3], 0, v[10:11]
	s_mov_b64 s[2:3], 0xd000000
	v_lshl_add_u64 v[2:3], v[2:3], 0, s[2:3]
	s_mul_hi_i32 s2, s12, 0xc00
	s_mul_i32 s3, s12, 0xc00
	v_or_b32_e32 v4, s3, v4
	v_mov_b32_e32 v5, s2
	s_mul_hi_i32 s2, s12, 0x600
	s_mul_i32 s3, s12, 0x600
	s_lshl_b64 s[0:1], s[12:13], 6
	s_ashr_i32 s15, s14, 31
	v_lshl_add_u64 v[4:5], v[4:5], 0, v[10:11]
	v_lshl_or_b32 v12, v6, 2, s3
	v_mov_b32_e32 v13, s2
	s_mov_b64 s[2:3], 0xe000500
	v_mov_b32_e32 v33, v11
	v_mov_b32_e32 v8, 0x60
	v_mul_u32_u24_e32 v10, 0xc0, v42
	v_lshl_or_b32 v0, v6, 3, s0
	v_mov_b32_e32 v1, s1
	s_lshl_b64 s[0:1], s[14:15], 6
	s_lshl_b64 s[6:7], s[14:15], 10
	s_mul_hi_i32 s9, s14, 0xc00
	s_mul_i32 s8, s14, 0xc00
	v_lshl_add_u64 v[6:7], v[12:13], 0, s[2:3]
	s_mul_hi_i32 s17, s14, 0x600
	s_mul_i32 s16, s14, 0x600
	v_mad_i64_i32 v[8:9], s[2:3], s12, v8, v[32:33]
	s_mul_hi_i32 s19, s14, 0x60
	s_mul_i32 s18, s14, 0x60
	v_lshl_add_u64 v[10:11], v[12:13], 0, v[10:11]
	s_mov_b32 s13, 0x5000000
	s_mov_b32 s15, 0xffff0000
	s_mov_b32 s20, 0x200000
	s_mov_b32 s21, 0x300000
	s_waitcnt lgkmcnt(0)
	s_movk_i32 s22, 0x7fff
	s_mov_b32 s23, 0xa800000
